# mixer-B (two-head GQA) key loop hand-rewritten like pass128: ping-pong halves, LDS writes+global loads in MFMA shadow, rowsum-guarded lazy max, hoisted address math
# speedup vs baseline: 1.0442x; 1.0442x over previous
; __device__ __forceinline__ void attn_pass2b(f32x16 (&o)[2][2], const bf16_t* qrow0, const bf16_t* Kb, const bf16_t* Vtb, int ka, int kb, LAS unsigned char* lds) {
;     const int tid = otid(), lane = tid & 63, r32 = lane & 31, hi = lane >> 5;
;     constexpr int kpitch = 128;
;     LAS bf16x8* ql = (LAS bf16x8*)(lds + 2 * ABUFB) + tid;
;     {
;         bf16x8 qf[8];
; #pragma unroll
;         for (int i = 0; i < 8; ++i) qf[i] = *(const bf16x8*)(qrow0 + 64 * (i >> 2) + 16 * (i & 3) + 8 * hi);
; #pragma unroll
;         for (int i = 0; i < 8; ++i) ql[i * 512] = qf[i];
;     }
; #pragma unroll
;     for (int rb = 0; rb < 2; ++rb)
; #pragma unroll
;         for (int i = 0; i < 2; ++i)
; #pragma unroll
;             for (int r = 0; r < 16; ++r) o[rb][i][r] = 0.f;
;     float mref = 0.f, lrun[2] = {0.f, 0.f};
;     f32x16 negm;
; #pragma unroll
;     for (int r = 0; r < 16; ++r) negm[r] = 0.f;
;     bool first = true;
;     const int nt = (kb - ka) >> 6;
;     ...
;     u32x4 kr, vr0;
;     { LANE_ADDR(); kr = *(const u32x4*)kg; vr0 = *(const u32x4*)vg; *(LAS u32x4*)(lds + kst) = kr; *(LAS u32x4*)(lds + vst) = vr0; }
;     __syncthreads();
;     for (int t = 0; t < nt; ++t) {
;         const bool more = (t + 1 < nt);
;         if (more) { LANE_ADDR(); kr = *(const u32x4*)(kg + (size_t)((t + 1) << 6) * kpitch); vr0 = *(const u32x4*)(vg + ((t + 1) << 6)); }
;         const LAS unsigned char* Kl = lds + (t & 1) * ABUFB;
;         const LAS unsigned char* Vl = Kl + KBUFB;
;         f32x16 p[2][2];
; #pragma unroll
;         for (int g = 0; g < 2; ++g) {
;             bf16x8 kf[4], qq[2][2];
; #pragma unroll
;             for (int d = 0; d < 2; ++d) {
;                 kf[2 * d] = *(const LAS bf16x8*)(Kl + (r32 * KP + 16 * (2 * g + d) + 8 * hi) * 2);
;                 kf[2 * d + 1] = *(const LAS bf16x8*)(Kl + ((32 + r32) * KP + 16 * (2 * g + d) + 8 * hi) * 2);
;                 qq[0][d] = ql[(2 * g + d) * 512]; qq[1][d] = ql[(4 + 2 * g + d) * 512];
;             }
;             __builtin_amdgcn_sched_barrier(0);
; #pragma unroll
;             for (int rb = 0; rb < 2; ++rb)
; #pragma unroll
;                 for (int d = 0; d < 2; ++d) {
;                     if (g == 0 && d == 0) { p[rb][0] = __builtin_amdgcn_mfma_f32_32x32x16_bf16(kf[0], qq[rb][0], negm, 0, 0, 0); p[rb][1] = __builtin_amdgcn_mfma_f32_32x32x16_bf16(kf[1], qq[rb][0], negm, 0, 0, 0); }
.LBB0_399:
	s_andn2_b64 vcc, exec, s[8:9]
	s_cbranch_vccnz .LBB0_414
	v_and_b32_e32 v172, 31, v215
	v_bfe_u32 v173, v215, 5, 1
	v_lshlrev_b32_e32 v173, 3, v173
	v_mul_u32_u24_e32 v174, 0x48, v172
	v_add_lshl_u32 v213, v173, v174, 1
	v_mul_u32_u24_e32 v212, 0x90, v172
	v_mbcnt_hi_u32_b32 v175, -1, v220
	v_and_b32_e32 v174, 64, v175
	v_xor_b32_e32 v176, 32, v175
	v_add_u32_e32 v177, 64, v174
	v_cmp_lt_i32_e32 vcc, v176, v177
	s_nop 1
	v_cndmask_b32_e32 v174, v175, v176, vcc
	v_lshlrev_b32_e32 v14, 2, v174
	v_ashrrev_i32_e32 v172, 3, v215
	v_lshlrev_b32_e32 v173, 4, v215
	v_and_b32_e32 v174, 0x70, v173
	v_mov_b32_e32 v175, 0
	v_add_u32_e32 v176, s94, v172
	v_ashrrev_i32_e32 v177, 31, v176
	v_lshlrev_b64 v[176:177], 8, v[176:177]
	v_lshl_add_u64 v[176:177], s[6:7], 0, v[176:177]
	v_lshl_add_u64 v[250:251], v[176:177], 0, v[174:175]
	s_lshl_b64 s[8:9], s[94:95], 1
	s_add_u32 s8, s4, s8
	s_addc_u32 s9, s5, s9
	v_mov_b64_e32 v[176:177], s[8:9]
	v_mad_i64_i32 v[176:177], s[10:11], v172, s58, v[176:177]
	v_lshl_add_u64 v[252:253], v[176:177], 0, v[174:175]
	v_lshlrev_b32_e32 v176, 1, v172
	v_lshrrev_b32_e32 v177, 1, v172
	v_and_b32_e32 v178, 0x1ffffff3, v172
	v_and_b32_e32 v176, 8, v176
	v_and_b32_e32 v177, 4, v177
	v_or3_b32 v178, v178, v176, v177
	v_lshlrev_b32_e32 v179, 3, v215
	v_and_b32_e32 v179, 56, v179
	v_mul_u32_u24_e32 v178, 0x48, v178
	v_mul_u32_u24_e32 v180, 0x48, v172
	v_add_lshl_u32 v254, v178, v179, 1
	v_add_lshl_u32 v221, v180, v179, 1
	v_mov_b32_e32 v16, 0
	v_mov_b32_e32 v17, 0
	v_mov_b32_e32 v18, 0
	v_mov_b32_e32 v19, 0
	v_mov_b32_e32 v20, 0
	v_mov_b32_e32 v21, 0
	v_mov_b32_e32 v22, 0
	v_mov_b32_e32 v23, 0
	v_mov_b32_e32 v24, 0
	v_mov_b32_e32 v25, 0
	v_mov_b32_e32 v26, 0
	v_mov_b32_e32 v27, 0
	v_mov_b32_e32 v28, 0
	v_mov_b32_e32 v29, 0
	v_mov_b32_e32 v30, 0
	v_mov_b32_e32 v31, 0
	v_mov_b32_e32 v32, 0
	v_mov_b32_e32 v33, 0
	v_mov_b32_e32 v34, 0
	v_mov_b32_e32 v35, 0
	v_mov_b32_e32 v36, 0
	v_mov_b32_e32 v37, 0
	v_mov_b32_e32 v38, 0
	v_mov_b32_e32 v39, 0
	v_mov_b32_e32 v40, 0
	v_mov_b32_e32 v41, 0
	v_mov_b32_e32 v42, 0
	v_mov_b32_e32 v43, 0
	v_mov_b32_e32 v44, 0
	v_mov_b32_e32 v45, 0
	v_mov_b32_e32 v46, 0
	v_mov_b32_e32 v47, 0
	v_mov_b32_e32 v48, 0
	v_mov_b32_e32 v49, 0
	v_mov_b32_e32 v50, 0
	v_mov_b32_e32 v51, 0
	v_mov_b32_e32 v52, 0
	v_mov_b32_e32 v53, 0
	v_mov_b32_e32 v54, 0
	v_mov_b32_e32 v55, 0
	v_mov_b32_e32 v56, 0
	v_mov_b32_e32 v57, 0
	v_mov_b32_e32 v58, 0
	v_mov_b32_e32 v59, 0
	v_mov_b32_e32 v60, 0
	v_mov_b32_e32 v61, 0
	v_mov_b32_e32 v62, 0
	v_mov_b32_e32 v63, 0
	v_mov_b32_e32 v64, 0
	v_mov_b32_e32 v65, 0
	v_mov_b32_e32 v66, 0
	v_mov_b32_e32 v67, 0
	v_mov_b32_e32 v68, 0
	v_mov_b32_e32 v69, 0
	v_mov_b32_e32 v70, 0
	v_mov_b32_e32 v71, 0
	v_mov_b32_e32 v72, 0
	v_mov_b32_e32 v73, 0
	v_mov_b32_e32 v74, 0
	v_mov_b32_e32 v75, 0
	v_mov_b32_e32 v76, 0
	v_mov_b32_e32 v77, 0
	v_mov_b32_e32 v78, 0
	v_mov_b32_e32 v79, 0
	v_mov_b32_e32 v80, 0
	v_mov_b32_e32 v81, 0
	v_mov_b32_e32 v82, 0
	v_mov_b32_e32 v83, 0
	v_mov_b32_e32 v84, 0
	v_mov_b32_e32 v85, 0
	v_mov_b32_e32 v86, 0
	v_mov_b32_e32 v87, 0
	v_mov_b32_e32 v88, 0
	v_mov_b32_e32 v89, 0
	v_mov_b32_e32 v90, 0
	v_mov_b32_e32 v91, 0
	v_mov_b32_e32 v92, 0
	v_mov_b32_e32 v93, 0
	v_mov_b32_e32 v94, 0
	v_mov_b32_e32 v95, 0
	v_mov_b32_e32 v214, 0
	v_mov_b32_e32 v170, 0
	v_mov_b32_e32 v171, 0
	s_cmp_lt_i32 s2, 2
	s_cbranch_scc1 .Lpb_pre_done
	s_movk_i32 s10, 0x4000
	s_mov_b32 s11, 0
	v_lshl_add_u64 v[172:173], v[250:251], 0, s[10:11]
	global_load_dwordx4 v[160:163], v[172:173], off
.Lpb_pre_done:
	v_readfirstlane_b32 s13, v215
	s_mov_b32 s3, 0
	s_lshr_b32 s13, s13, 8
	s_cmp_eq_u32 s13, 0
	s_cbranch_scc1 .Lpb_X
	s_barrier
.Lpb_X:
	s_setprio 1
	s_and_b32 s1, s3, 1
	s_mul_i32 s8, s1, 0x6c00
	s_sub_i32 s9, 0x6c00, s8
	v_add_u32_e32 v156, s8, v213
	v_add3_u32 v157, s9, v168, v212
	s_cmp_eq_u32 s3, 0
	s_cbranch_scc1 .Lpb_Xfirst
	s_cmp_ge_i32 s3, s2
	s_cbranch_scc1 .Lpb_Xlast
	ds_read_b128 v[96:99], v157 offset:9216
	ds_read_b128 v[100:103], v157 offset:9248
	ds_read_b128 v[104:107], v157 offset:9280
	ds_read_b128 v[108:111], v157 offset:9312
	ds_read_b128 v[112:115], v157 offset:13824
	ds_read_b128 v[116:119], v157 offset:13856
	ds_read_b128 v[120:123], v157 offset:13888
	ds_read_b128 v[124:127], v157 offset:13920
	ds_read_b128 v[172:175], v156
	ds_read_b128 v[176:179], v156 offset:4608
	v_add_u32_e32 v158, s9, v254
	v_add_u32_e32 v159, s8, v221
	s_waitcnt lgkmcnt(9)
	v_mfma_f32_32x32x16_bf16 v[48:63], v[96:99], v[222:225], v[48:63]
	v_mfma_f32_32x32x16_bf16 v[16:31], v[96:99], v[238:241], v[16:31]
	ds_read_b128 v[180:183], v156 offset:32
	ds_read_b128 v[188:191], v156 offset:4640
	s_waitcnt lgkmcnt(10)
	v_mfma_f32_32x32x16_bf16 v[48:63], v[100:103], v[226:229], v[48:63]
	v_mfma_f32_32x32x16_bf16 v[16:31], v[100:103], v[242:245], v[16:31]
	ds_read_b128 v[192:195], v156 offset:64
	ds_read_b128 v[196:199], v156 offset:4672
	s_waitcnt lgkmcnt(11)
	v_mfma_f32_32x32x16_bf16 v[48:63], v[104:107], v[230:233], v[48:63]
	v_mfma_f32_32x32x16_bf16 v[16:31], v[104:107], v[246:249], v[16:31]
	ds_read_b128 v[200:203], v156 offset:96
	ds_read_b128 v[204:207], v156 offset:4704
	s_waitcnt lgkmcnt(12)
	v_mfma_f32_32x32x16_bf16 v[48:63], v[108:111], v[234:237], v[48:63]
	v_mfma_f32_32x32x16_bf16 v[16:31], v[108:111], v[216:219], v[16:31]
	ds_read_b128 v[2:5], v169 offset:55296
	ds_read_b128 v[6:9], v169 offset:63488
	s_waitcnt vmcnt(0)
	s_waitcnt lgkmcnt(13)
	v_mfma_f32_32x32x16_bf16 v[64:79], v[112:115], v[222:225], v[64:79]
	v_mfma_f32_32x32x16_bf16 v[32:47], v[112:115], v[238:241], v[32:47]
	ds_write_b128 v158, v[160:163]
	ds_read_b128 v[10:13], v187 offset:16384
	s_waitcnt lgkmcnt(14)
	v_mfma_f32_32x32x16_bf16 v[64:79], v[116:119], v[226:229], v[64:79]
	v_mfma_f32_32x32x16_bf16 v[32:47], v[116:119], v[242:245], v[32:47]
	ds_write_b128 v159, v[164:167] offset:9216
	s_waitcnt lgkmcnt(14)
	v_mfma_f32_32x32x16_bf16 v[64:79], v[120:123], v[230:233], v[64:79]
	v_mfma_f32_32x32x16_bf16 v[32:47], v[120:123], v[246:249], v[32:47]
	ds_read_b128 v[208:211], v187 offset:24576
	s_waitcnt lgkmcnt(14)
	v_mfma_f32_32x32x16_bf16 v[64:79], v[124:127], v[234:237], v[64:79]
	v_mfma_f32_32x32x16_bf16 v[32:47], v[124:127], v[216:219], v[32:47]
	s_add_i32 s1, s3, 1
	s_cmp_ge_i32 s1, s2
	s_cbranch_scc1 .Lpb_noload_mid
	s_lshl_b32 s10, s1, 7
	s_mov_b32 s11, 0
	v_lshl_add_u64 v[96:97], v[252:253], 0, s[10:11]
	global_load_dwordx4 v[164:167], v[96:97], off
	s_add_i32 s1, s3, 2
	s_cmp_ge_i32 s1, s2
	s_cbranch_scc1 .Lpb_noload_mid
	s_lshl_b32 s10, s1, 14
	v_lshl_add_u64 v[96:97], v[250:251], 0, s[10:11]
	global_load_dwordx4 v[160:163], v[96:97], off
; #define LAS __attribute__((address_space(3)))
; __device__ __forceinline__ void attn_pass2b(f32x16 (&o)[2][2], const bf16_t* qrow0, const bf16_t* Kb, const bf16_t* Vtb, int ka, int kb, LAS unsigned char* lds) {
;     ...
;     for (int t = 0; t < nt; ++t) {
;         const bool more = (t + 1 < nt);
;         if (more) { LANE_ADDR(); kr = *(const u32x4*)(kg + (size_t)((t + 1) << 6) * kpitch); vr0 = *(const u32x4*)(vg + ((t + 1) << 6)); }
;         const LAS unsigned char* Kl = lds + (t & 1) * ABUFB;
;         const LAS unsigned char* Vl = Kl + KBUFB;
;         f32x16 p[2][2];
; #pragma unroll
;         for (int g = 0; g < 2; ++g) {
;             bf16x8 kf[4], qq[2][2];
; #pragma unroll
;             for (int d = 0; d < 2; ++d) {
;                 kf[2 * d] = *(const LAS bf16x8*)(Kl + (r32 * KP + 16 * (2 * g + d) + 8 * hi) * 2);
;                 kf[2 * d + 1] = *(const LAS bf16x8*)(Kl + ((32 + r32) * KP + 16 * (2 * g + d) + 8 * hi) * 2);
;                 qq[0][d] = ql[(2 * g + d) * 512]; qq[1][d] = ql[(4 + 2 * g + d) * 512];
;             }
;             __builtin_amdgcn_sched_barrier(0);
; #pragma unroll
;             for (int rb = 0; rb < 2; ++rb)
; #pragma unroll
;                 for (int d = 0; d < 2; ++d) {
;                     if (g == 0 && d == 0) { p[rb][0] = __builtin_amdgcn_mfma_f32_32x32x16_bf16(kf[0], qq[rb][0], negm, 0, 0, 0); p[rb][1] = __builtin_amdgcn_mfma_f32_32x32x16_bf16(kf[1], qq[rb][0], negm, 0, 0, 0); }
;                     else { p[rb][0] = __builtin_amdgcn_mfma_f32_32x32x16_bf16(kf[2 * d], qq[rb][d], p[rb][0], 0, 0, 0); p[rb][1] = __builtin_amdgcn_mfma_f32_32x32x16_bf16(kf[2 * d + 1], qq[rb][d], p[rb][1], 0, 0, 0); }
;                 }
;             __builtin_amdgcn_sched_barrier(0);
;         }
;     ...
;         if (more) { LANE_ADDR(); const unsigned bo = ((t + 1) & 1) * ABUFB; *(LAS u32x4*)(lds + bo + kst) = kr; *(LAS u32x4*)(lds + bo + vst) = vr0; }
.Lpb_noload_mid:
	s_waitcnt lgkmcnt(5)
	v_mfma_f32_32x32x16_bf16 v[128:143], v[172:175], v[2:5], v[80:95]
	v_mfma_f32_32x32x16_bf16 v[144:159], v[176:179], v[2:5], v[80:95]
	ds_read_b128 v[2:5], v187 offset:32768
	s_waitcnt lgkmcnt(5)
	v_mfma_f32_32x32x16_bf16 v[128:143], v[180:183], v[6:9], v[128:143]
	v_mfma_f32_32x32x16_bf16 v[144:159], v[188:191], v[6:9], v[144:159]
	ds_read_b128 v[6:9], v187 offset:40960
	s_waitcnt lgkmcnt(4)
	v_mfma_f32_32x32x16_bf16 v[128:143], v[192:195], v[10:13], v[128:143]
	v_mfma_f32_32x32x16_bf16 v[144:159], v[196:199], v[10:13], v[144:159]
	ds_read_b128 v[10:13], v187 offset:49152
	s_waitcnt lgkmcnt(3)
	v_mfma_f32_32x32x16_bf16 v[128:143], v[200:203], v[208:211], v[128:143]
	v_mfma_f32_32x32x16_bf16 v[144:159], v[204:207], v[208:211], v[144:159]
	ds_read_b128 v[208:211], v187 offset:57344
	s_waitcnt lgkmcnt(3)
	v_mfma_f32_32x32x16_bf16 v[112:127], v[172:175], v[2:5], v[80:95]
	v_mfma_f32_32x32x16_bf16 v[96:111], v[176:179], v[2:5], v[80:95]
	s_waitcnt lgkmcnt(2)
	v_mfma_f32_32x32x16_bf16 v[112:127], v[180:183], v[6:9], v[112:127]
	v_mfma_f32_32x32x16_bf16 v[96:111], v[188:191], v[6:9], v[96:111]
	s_waitcnt lgkmcnt(1)
	v_mfma_f32_32x32x16_bf16 v[112:127], v[192:195], v[10:13], v[112:127]
	v_mfma_f32_32x32x16_bf16 v[96:111], v[196:199], v[10:13], v[96:111]
	s_waitcnt lgkmcnt(0)
	v_mfma_f32_32x32x16_bf16 v[112:127], v[200:203], v[208:211], v[112:127]
	v_mfma_f32_32x32x16_bf16 v[96:111], v[204:207], v[208:211], v[96:111]
	s_barrier
	s_branch .Lpb_Y
.Lpb_Xfirst:
	ds_read_b128 v[172:175], v156
	ds_read_b128 v[176:179], v156 offset:4608
	ds_read_b128 v[180:183], v156 offset:32
	ds_read_b128 v[188:191], v156 offset:4640
	ds_read_b128 v[192:195], v156 offset:64
	ds_read_b128 v[196:199], v156 offset:4672
	ds_read_b128 v[200:203], v156 offset:96
	ds_read_b128 v[204:207], v156 offset:4704
	ds_read_b128 v[2:5], v169 offset:55296
	ds_read_b128 v[6:9], v169 offset:63488
	ds_read_b128 v[10:13], v187 offset:16384
	ds_read_b128 v[208:211], v187 offset:24576
	s_waitcnt lgkmcnt(3)
	v_mfma_f32_32x32x16_bf16 v[128:143], v[172:175], v[2:5], v[80:95]
	v_mfma_f32_32x32x16_bf16 v[144:159], v[176:179], v[2:5], v[80:95]
	ds_read_b128 v[2:5], v187 offset:32768
	s_waitcnt lgkmcnt(3)
	v_mfma_f32_32x32x16_bf16 v[128:143], v[180:183], v[6:9], v[128:143]
	v_mfma_f32_32x32x16_bf16 v[144:159], v[188:191], v[6:9], v[144:159]
	ds_read_b128 v[6:9], v187 offset:40960
	s_waitcnt lgkmcnt(3)
	v_mfma_f32_32x32x16_bf16 v[128:143], v[192:195], v[10:13], v[128:143]
	v_mfma_f32_32x32x16_bf16 v[144:159], v[196:199], v[10:13], v[144:159]
	ds_read_b128 v[10:13], v187 offset:49152
	s_waitcnt lgkmcnt(3)
	v_mfma_f32_32x32x16_bf16 v[128:143], v[200:203], v[208:211], v[128:143]
	v_mfma_f32_32x32x16_bf16 v[144:159], v[204:207], v[208:211], v[144:159]
	ds_read_b128 v[208:211], v187 offset:57344
	s_waitcnt lgkmcnt(3)
	v_mfma_f32_32x32x16_bf16 v[112:127], v[172:175], v[2:5], v[80:95]
	v_mfma_f32_32x32x16_bf16 v[96:111], v[176:179], v[2:5], v[80:95]
	s_waitcnt lgkmcnt(2)
	v_mfma_f32_32x32x16_bf16 v[112:127], v[180:183], v[6:9], v[112:127]
	v_mfma_f32_32x32x16_bf16 v[96:111], v[188:191], v[6:9], v[96:111]
	s_waitcnt lgkmcnt(1)
	v_mfma_f32_32x32x16_bf16 v[112:127], v[192:195], v[10:13], v[112:127]
	v_mfma_f32_32x32x16_bf16 v[96:111], v[196:199], v[10:13], v[96:111]
	s_waitcnt lgkmcnt(0)
	v_mfma_f32_32x32x16_bf16 v[112:127], v[200:203], v[208:211], v[112:127]
	v_mfma_f32_32x32x16_bf16 v[96:111], v[204:207], v[208:211], v[96:111]
	s_waitcnt vmcnt(0)
	s_cmp_lt_i32 s2, 2
	s_cbranch_scc1 .Lpb_nokw
	v_add_u32_e32 v172, s9, v254
	ds_write_b128 v172, v[160:163]
.Lpb_nokw:
	s_add_i32 s1, s3, 1
	s_cmp_ge_i32 s1, s2
	s_cbranch_scc1 .Lpb_noload_first
	s_lshl_b32 s10, s1, 7
	s_mov_b32 s11, 0
	v_lshl_add_u64 v[172:173], v[252:253], 0, s[10:11]
	global_load_dwordx4 v[164:167], v[172:173], off
	s_add_i32 s1, s3, 2
	s_cmp_ge_i32 s1, s2
	s_cbranch_scc1 .Lpb_noload_first
	s_lshl_b32 s10, s1, 14
	v_lshl_add_u64 v[172:173], v[250:251], 0, s[10:11]
	global_load_dwordx4 v[160:163], v[172:173], off

; #define MX3(a, b, c) __builtin_fmaxf(__builtin_fmaxf((a), (b)), (c))
; __device__ __forceinline__ void attn_pass2b(f32x16 (&o)[2][2], const bf16_t* qrow0, const bf16_t* Kb, const bf16_t* Vtb, int ka, int kb, LAS unsigned char* lds) {
;     ...
;         float mx;
;         {
;             float ma = MX3(p[0][0][0], p[0][0][1], p[0][1][0]), mb = MX3(p[1][0][0], p[1][0][1], p[1][1][0]);
; #pragma unroll
;             for (int rb = 0; rb < 2; ++rb) {
;                 const f32x16& p0 = p[rb][0]; const f32x16& p1 = p[rb][1];
;                 ma = MX3(ma, p0[2], p0[3]); mb = MX3(mb, p1[1], p1[2]); ma = MX3(ma, p1[3], p0[4]);
; #pragma unroll
;                 for (int r = 5; r < 16; r += 2) { ma = MX3(ma, p0[r], p0[r + (r < 15 ? 1 : 0)]); mb = MX3(mb, p1[r - 1], p1[r]); }
;             }
;             mx = fmaxf(ma, mb);
;             mx = fmaxf(mx, __shfl_xor(mx, 32));
;         }
;     ...
;         if (first || __any(mx > 8.f)) {
;             const float dl = first ? mx : fmaxf(mx, 0.f);
;             const float alpha = first ? 1.f : __builtin_amdgcn_exp2f(-dl);
;             mref += dl; lrun[0] *= alpha; lrun[1] *= alpha;
; #pragma unroll
;             for (int r = 0; r < 16; ++r) negm[r] = -mref;
; #pragma unroll
;             for (int rb = 0; rb < 2; ++rb) {
; #pragma unroll
;                 for (int r = 0; r < 16; ++r) { p[rb][0][r] -= dl; p[rb][1][r] -= dl; }
; #pragma unroll
;                 for (int i = 0; i < 2; ++i)
; #pragma unroll
;                     for (int r = 0; r < 16; ++r) o[rb][i][r] *= alpha;
;             }
;             first = false;
;         }
;         bf16x8 pk[2][4];
; #pragma unroll
;         for (int rb = 0; rb < 2; ++rb) {
;             f32x16& p0 = p[rb][0]; f32x16& p1 = p[rb][1];
;             float rs0 = 0.f, rs1 = 0.f;
; #pragma unroll
;             for (int r = 0; r < 16; ++r) { p0[r] = __builtin_amdgcn_exp2f(p0[r]); p1[r] = __builtin_amdgcn_exp2f(p1[r]); rs0 += p0[r]; rs1 += p1[r]; }
;             lrun[rb] += rs0 + rs1;
;             u32x4 w;
;             w.x = cvtpk(p0[0], p0[1]); w.y = cvtpk(p0[2], p0[3]); w.z = cvtpk(p0[4], p0[5]); w.w = cvtpk(p0[6], p0[7]); pk[rb][0] = __builtin_bit_cast(bf16x8, w);
;             w.x = cvtpk(p0[8], p0[9]); w.y = cvtpk(p0[10], p0[11]); w.z = cvtpk(p0[12], p0[13]); w.w = cvtpk(p0[14], p0[15]); pk[rb][1] = __builtin_bit_cast(bf16x8, w);
.Lpb_Y:
	s_setprio 0
	s_nop 7
	s_cmp_eq_u32 s3, 0
	s_cbranch_scc1 .Lpb_slow
	v_exp_f32_e32 v172, v128
	v_exp_f32_e32 v173, v129
	v_exp_f32_e32 v174, v130
	v_exp_f32_e32 v175, v131
	v_exp_f32_e32 v176, v132
	v_exp_f32_e32 v177, v133
	v_exp_f32_e32 v178, v134
	v_exp_f32_e32 v179, v135
	v_exp_f32_e32 v180, v136
	v_exp_f32_e32 v181, v137
	v_exp_f32_e32 v182, v138
	v_exp_f32_e32 v183, v139
	v_exp_f32_e32 v188, v140
	v_exp_f32_e32 v189, v141
	v_exp_f32_e32 v190, v142
	v_exp_f32_e32 v191, v143
	v_cvt_pk_bf16_f32 v222, v172, v173
	v_add_f32_e32 v2, v172, v174
	v_add_f32_e32 v6, v173, v175
	v_cvt_pk_bf16_f32 v223, v174, v175
	v_cvt_pk_bf16_f32 v224, v176, v177
	v_add_f32_e32 v2, v176, v2
	v_add_f32_e32 v6, v177, v6
	v_cvt_pk_bf16_f32 v225, v178, v179
	v_add_f32_e32 v2, v178, v2
	v_add_f32_e32 v6, v179, v6
	v_cvt_pk_bf16_f32 v226, v180, v181
	v_add_f32_e32 v2, v180, v2
	v_add_f32_e32 v6, v181, v6
	v_cvt_pk_bf16_f32 v227, v182, v183
	v_add_f32_e32 v2, v182, v2
	v_add_f32_e32 v6, v183, v6
	v_cvt_pk_bf16_f32 v228, v188, v189
	v_add_f32_e32 v2, v188, v2
	v_add_f32_e32 v6, v189, v6
	v_cvt_pk_bf16_f32 v229, v190, v191
	v_add_f32_e32 v2, v190, v2
	v_add_f32_e32 v6, v191, v6
	v_exp_f32_e32 v192, v144
	v_exp_f32_e32 v193, v145
	v_exp_f32_e32 v194, v146
	v_exp_f32_e32 v195, v147
	v_exp_f32_e32 v196, v148
	v_exp_f32_e32 v197, v149
	v_exp_f32_e32 v198, v150
	v_exp_f32_e32 v199, v151
	v_exp_f32_e32 v200, v152
	v_exp_f32_e32 v201, v153
	v_exp_f32_e32 v202, v154
	v_exp_f32_e32 v203, v155
	v_exp_f32_e32 v204, v156
	v_exp_f32_e32 v205, v157
	v_exp_f32_e32 v206, v158
	v_exp_f32_e32 v207, v159
	v_cvt_pk_bf16_f32 v230, v192, v193
	v_add_f32_e32 v3, v192, v194
	v_add_f32_e32 v7, v193, v195
	v_cvt_pk_bf16_f32 v231, v194, v195
	v_cvt_pk_bf16_f32 v232, v196, v197
	v_add_f32_e32 v3, v196, v3
	v_add_f32_e32 v7, v197, v7
	v_cvt_pk_bf16_f32 v233, v198, v199
	v_add_f32_e32 v3, v198, v3
	v_add_f32_e32 v7, v199, v7
	v_cvt_pk_bf16_f32 v234, v200, v201
	v_add_f32_e32 v3, v200, v3
	v_add_f32_e32 v7, v201, v7
	v_cvt_pk_bf16_f32 v235, v202, v203
	v_add_f32_e32 v3, v202, v3
	v_add_f32_e32 v7, v203, v7
	v_cvt_pk_bf16_f32 v236, v204, v205
	v_add_f32_e32 v3, v204, v3
	v_add_f32_e32 v7, v205, v7
	v_cvt_pk_bf16_f32 v237, v206, v207
	v_add_f32_e32 v3, v206, v3
	v_add_f32_e32 v7, v207, v7
	v_exp_f32_e32 v172, v112
	v_exp_f32_e32 v173, v113
	v_exp_f32_e32 v174, v114
	v_exp_f32_e32 v175, v115
	v_exp_f32_e32 v176, v116
	v_exp_f32_e32 v177, v117
	v_exp_f32_e32 v178, v118
	v_exp_f32_e32 v179, v119
	v_exp_f32_e32 v180, v120
	v_exp_f32_e32 v181, v121
	v_exp_f32_e32 v182, v122
	v_exp_f32_e32 v183, v123
	v_exp_f32_e32 v188, v124
	v_exp_f32_e32 v189, v125
	v_exp_f32_e32 v190, v126
	v_exp_f32_e32 v191, v127
	v_cvt_pk_bf16_f32 v238, v172, v173
	v_add_f32_e32 v4, v172, v174
	v_add_f32_e32 v8, v173, v175
	v_cvt_pk_bf16_f32 v239, v174, v175
	v_cvt_pk_bf16_f32 v240, v176, v177
	v_add_f32_e32 v4, v176, v4
	v_add_f32_e32 v8, v177, v8
	v_cvt_pk_bf16_f32 v241, v178, v179
	v_add_f32_e32 v4, v178, v4
	v_add_f32_e32 v8, v179, v8
	v_cvt_pk_bf16_f32 v242, v180, v181
	v_add_f32_e32 v4, v180, v4
	v_add_f32_e32 v8, v181, v8
	v_cvt_pk_bf16_f32 v243, v182, v183
	v_add_f32_e32 v4, v182, v4
	v_add_f32_e32 v8, v183, v8
	v_cvt_pk_bf16_f32 v244, v188, v189
	v_add_f32_e32 v4, v188, v4
	v_add_f32_e32 v8, v189, v8
	v_cvt_pk_bf16_f32 v245, v190, v191
	v_add_f32_e32 v4, v190, v4
	v_add_f32_e32 v8, v191, v8
	v_exp_f32_e32 v192, v96
	v_exp_f32_e32 v193, v97
	v_exp_f32_e32 v194, v98
	v_exp_f32_e32 v195, v99
	v_exp_f32_e32 v196, v100
	v_exp_f32_e32 v197, v101
	v_exp_f32_e32 v198, v102
	v_exp_f32_e32 v199, v103
	v_exp_f32_e32 v200, v104
	v_exp_f32_e32 v201, v105
	v_exp_f32_e32 v202, v106
	v_exp_f32_e32 v203, v107
	v_exp_f32_e32 v204, v108
	v_exp_f32_e32 v205, v109
	v_exp_f32_e32 v206, v110
	v_exp_f32_e32 v207, v111
	v_cvt_pk_bf16_f32 v246, v192, v193
	v_add_f32_e32 v5, v192, v194
	v_add_f32_e32 v9, v193, v195
	v_cvt_pk_bf16_f32 v247, v194, v195
	v_cvt_pk_bf16_f32 v248, v196, v197
	v_add_f32_e32 v5, v196, v5
	v_add_f32_e32 v9, v197, v9
	v_cvt_pk_bf16_f32 v249, v198, v199
	v_add_f32_e32 v5, v198, v5
	v_add_f32_e32 v9, v199, v9
	v_cvt_pk_bf16_f32 v216, v200, v201
	v_add_f32_e32 v5, v200, v5
	v_add_f32_e32 v9, v201, v9
	v_cvt_pk_bf16_f32 v217, v202, v203
	v_add_f32_e32 v5, v202, v5
	v_add_f32_e32 v9, v203, v9
	v_cvt_pk_bf16_f32 v218, v204, v205
	v_add_f32_e32 v5, v204, v5
	v_add_f32_e32 v9, v205, v9
	v_cvt_pk_bf16_f32 v219, v206, v207
	v_add_f32_e32 v5, v206, v5
	v_add_f32_e32 v9, v207, v9
	v_add_f32_e32 v2, v6, v2
	v_add_f32_e32 v3, v7, v3
	v_add_f32_e32 v4, v8, v4
	v_add_f32_e32 v5, v9, v5
	v_add_f32_e32 v2, v3, v2
	v_add_f32_e32 v4, v5, v4
	v_max_f32_e32 v6, v2, v4
	v_cmp_lt_f32_e32 vcc, 0x43800000, v6
	s_nop 0
	s_cbranch_vccnz .Lpb_slow
.Lpb_tail:
	v_add_f32_e32 v171, v171, v2
	v_add_f32_e32 v170, v170, v4
	s_add_i32 s3, s3, 1
	s_barrier
	s_branch .Lpb_X
.Lpb_slow:
	v_max3_f32 v8, v128, v129, v130
	v_max3_f32 v9, v131, v132, v133
	v_max3_f32 v8, v8, v134, v135
	v_max3_f32 v9, v9, v136, v137
	v_max3_f32 v8, v8, v138, v139
	v_max3_f32 v9, v9, v140, v141
	v_max3_f32 v8, v8, v142, v143
	v_max3_f32 v9, v9, v144, v145
	v_max3_f32 v8, v8, v146, v147
	v_max3_f32 v9, v9, v148, v149
	v_max3_f32 v8, v8, v150, v151
	v_max3_f32 v9, v9, v152, v153
	v_max3_f32 v8, v8, v154, v155
	v_max3_f32 v9, v9, v156, v157
	v_max3_f32 v8, v8, v158, v159
	v_max3_f32 v9, v9, v112, v113
	v_max3_f32 v8, v8, v114, v115
	v_max3_f32 v9, v9, v116, v117
	v_max3_f32 v8, v8, v118, v119
	v_max3_f32 v9, v9, v120, v121
	v_max3_f32 v8, v8, v122, v123
	v_max3_f32 v9, v9, v124, v125
	v_max3_f32 v8, v8, v126, v127
	v_max3_f32 v9, v9, v96, v97
	v_max3_f32 v8, v8, v98, v99
	v_max3_f32 v9, v9, v100, v101
	v_max3_f32 v8, v8, v102, v103
	v_max3_f32 v9, v9, v104, v105
	v_max3_f32 v8, v8, v106, v107
	v_max3_f32 v9, v9, v108, v109
	v_max3_f32 v8, v8, v110, v111
	v_max_f32_e32 v8, v8, v9
	ds_bpermute_b32 v9, v14, v8
	s_waitcnt lgkmcnt(0)
	v_max_f32_e32 v9, v9, v9
	v_max_f32_e32 v8, v8, v9
	v_cmp_lt_f32_e32 vcc, s73, v8
	s_cmp_eq_u32 s3, 0
	s_cbranch_scc1 .Lpb_resc
	s_cbranch_vccz .Lpb_tail
; __device__ __forceinline__ unsigned cvtpk(float lo, float hi) { const f32x2_t v = {lo, hi}; const bf16x2_t b = __builtin_convertvector(v, bf16x2_t); return __builtin_bit_cast(unsigned, b); }
; __device__ __forceinline__ void attn_pass2b(f32x16 (&o)[2][2], const bf16_t* qrow0, const bf16_t* Kb, const bf16_t* Vtb, int ka, int kb, LAS unsigned char* lds) {
;     ...
;         if (first || __any(mx > 8.f)) {
;             const float dl = first ? mx : fmaxf(mx, 0.f);
;             const float alpha = first ? 1.f : __builtin_amdgcn_exp2f(-dl);
;             mref += dl; lrun[0] *= alpha; lrun[1] *= alpha;
; #pragma unroll
;             for (int r = 0; r < 16; ++r) negm[r] = -mref;
; #pragma unroll
;             for (int rb = 0; rb < 2; ++rb) {
; #pragma unroll
;                 for (int r = 0; r < 16; ++r) { p[rb][0][r] -= dl; p[rb][1][r] -= dl; }
; #pragma unroll
;                 for (int i = 0; i < 2; ++i)
; #pragma unroll
;                     for (int r = 0; r < 16; ++r) o[rb][i][r] *= alpha;
;             }
;             first = false;
;         }
;         bf16x8 pk[2][4];
; #pragma unroll
;         for (int rb = 0; rb < 2; ++rb) {
;             f32x16& p0 = p[rb][0]; f32x16& p1 = p[rb][1];
;             float rs0 = 0.f, rs1 = 0.f;
; #pragma unroll
;             for (int r = 0; r < 16; ++r) { p0[r] = __builtin_amdgcn_exp2f(p0[r]); p1[r] = __builtin_amdgcn_exp2f(p1[r]); rs0 += p0[r]; rs1 += p1[r]; }
;             lrun[rb] += rs0 + rs1;
;             u32x4 w;
;             w.x = cvtpk(p0[0], p0[1]); w.y = cvtpk(p0[2], p0[3]); w.z = cvtpk(p0[4], p0[5]); w.w = cvtpk(p0[6], p0[7]); pk[rb][0] = __builtin_bit_cast(bf16x8, w);
;             w.x = cvtpk(p0[8], p0[9]); w.y = cvtpk(p0[10], p0[11]); w.z = cvtpk(p0[12], p0[13]); w.w = cvtpk(p0[14], p0[15]); pk[rb][1] = __builtin_bit_cast(bf16x8, w);
;             w.x = cvtpk(p1[0], p1[1]); w.y = cvtpk(p1[2], p1[3]); w.z = cvtpk(p1[4], p1[5]); w.w = cvtpk(p1[6], p1[7]); pk[rb][2] = __builtin_bit_cast(bf16x8, w);
;             w.x = cvtpk(p1[8], p1[9]); w.y = cvtpk(p1[10], p1[11]); w.z = cvtpk(p1[12], p1[13]); w.w = cvtpk(p1[14], p1[15]); pk[rb][3] = __builtin_bit_cast(bf16x8, w);
;         }
.Lpb_resc:
	s_cmp_eq_u32 s3, 0
	s_cselect_b64 vcc, -1, 0
	v_max_f32_e32 v8, v8, v8
	v_max_f32_e32 v9, 0, v8
	s_nop 1
	v_cndmask_b32_e32 v8, v9, v8, vcc
	v_exp_f32_e64 v9, -v8
	v_add_f32_e32 v214, v214, v8
	s_nop 0
	v_cndmask_b32_e64 v9, v9, 1.0, vcc
	v_sub_f32_e32 v128, v128, v8
	v_sub_f32_e32 v129, v129, v8
	v_sub_f32_e32 v130, v130, v8
	v_sub_f32_e32 v131, v131, v8
	v_sub_f32_e32 v132, v132, v8
	v_sub_f32_e32 v133, v133, v8
	v_sub_f32_e32 v134, v134, v8
	v_sub_f32_e32 v135, v135, v8
	v_sub_f32_e32 v136, v136, v8
	v_sub_f32_e32 v137, v137, v8
	v_sub_f32_e32 v138, v138, v8
	v_sub_f32_e32 v139, v139, v8
	v_sub_f32_e32 v140, v140, v8
	v_sub_f32_e32 v141, v141, v8
	v_sub_f32_e32 v142, v142, v8
	v_sub_f32_e32 v143, v143, v8
	v_sub_f32_e32 v144, v144, v8
	v_sub_f32_e32 v145, v145, v8
	v_sub_f32_e32 v146, v146, v8
	v_sub_f32_e32 v147, v147, v8
	v_sub_f32_e32 v148, v148, v8
	v_sub_f32_e32 v149, v149, v8
	v_sub_f32_e32 v150, v150, v8
	v_sub_f32_e32 v151, v151, v8
	v_sub_f32_e32 v152, v152, v8
	v_sub_f32_e32 v153, v153, v8
	v_sub_f32_e32 v154, v154, v8
	v_sub_f32_e32 v155, v155, v8
	v_sub_f32_e32 v156, v156, v8
	v_sub_f32_e32 v157, v157, v8
	v_sub_f32_e32 v158, v158, v8
	v_sub_f32_e32 v159, v159, v8
	v_sub_f32_e32 v112, v112, v8
	v_sub_f32_e32 v113, v113, v8
	v_sub_f32_e32 v114, v114, v8
	v_sub_f32_e32 v115, v115, v8
	v_sub_f32_e32 v116, v116, v8
	v_sub_f32_e32 v117, v117, v8
	v_sub_f32_e32 v118, v118, v8
	v_sub_f32_e32 v119, v119, v8
	v_sub_f32_e32 v120, v120, v8
	v_sub_f32_e32 v121, v121, v8
	v_sub_f32_e32 v122, v122, v8
	v_sub_f32_e32 v123, v123, v8
	v_sub_f32_e32 v124, v124, v8
	v_sub_f32_e32 v125, v125, v8
	v_sub_f32_e32 v126, v126, v8
	v_sub_f32_e32 v127, v127, v8
	v_sub_f32_e32 v96, v96, v8
	v_sub_f32_e32 v97, v97, v8
	v_sub_f32_e32 v98, v98, v8
	v_sub_f32_e32 v99, v99, v8
	v_sub_f32_e32 v100, v100, v8
	v_sub_f32_e32 v101, v101, v8
	v_sub_f32_e32 v102, v102, v8
	v_sub_f32_e32 v103, v103, v8
	v_sub_f32_e32 v104, v104, v8
	v_sub_f32_e32 v105, v105, v8
	v_sub_f32_e32 v106, v106, v8
	v_sub_f32_e32 v107, v107, v8
	v_sub_f32_e32 v108, v108, v8
	v_sub_f32_e32 v109, v109, v8
	v_sub_f32_e32 v110, v110, v8
	v_sub_f32_e32 v111, v111, v8
	v_mul_f32_e32 v16, v16, v9
	v_mul_f32_e32 v17, v17, v9
	v_mul_f32_e32 v18, v18, v9
	v_mul_f32_e32 v19, v19, v9
	v_mul_f32_e32 v20, v20, v9
	v_mul_f32_e32 v21, v21, v9
	v_mul_f32_e32 v22, v22, v9
	v_mul_f32_e32 v23, v23, v9
	v_mul_f32_e32 v24, v24, v9
	v_mul_f32_e32 v25, v25, v9
	v_mul_f32_e32 v26, v26, v9
	v_mul_f32_e32 v27, v27, v9
	v_mul_f32_e32 v28, v28, v9
	v_mul_f32_e32 v29, v29, v9
	v_mul_f32_e32 v30, v30, v9
	v_mul_f32_e32 v31, v31, v9
	v_mul_f32_e32 v32, v32, v9
	v_mul_f32_e32 v33, v33, v9
	v_mul_f32_e32 v34, v34, v9
	v_mul_f32_e32 v35, v35, v9
	v_mul_f32_e32 v36, v36, v9
	v_mul_f32_e32 v37, v37, v9
	v_mul_f32_e32 v38, v38, v9
	v_mul_f32_e32 v39, v39, v9
	v_mul_f32_e32 v40, v40, v9
	v_mul_f32_e32 v41, v41, v9
	v_mul_f32_e32 v42, v42, v9
	v_mul_f32_e32 v43, v43, v9
	v_mul_f32_e32 v44, v44, v9
	v_mul_f32_e32 v45, v45, v9
	v_mul_f32_e32 v46, v46, v9
	v_mul_f32_e32 v47, v47, v9
	v_mul_f32_e32 v48, v48, v9
	v_mul_f32_e32 v49, v49, v9
	v_mul_f32_e32 v50, v50, v9
	v_mul_f32_e32 v51, v51, v9
	v_mul_f32_e32 v52, v52, v9
	v_mul_f32_e32 v53, v53, v9
	v_mul_f32_e32 v54, v54, v9
	v_mul_f32_e32 v55, v55, v9
	v_mul_f32_e32 v56, v56, v9
	v_mul_f32_e32 v57, v57, v9
	v_mul_f32_e32 v58, v58, v9
	v_mul_f32_e32 v59, v59, v9
	v_mul_f32_e32 v60, v60, v9
	v_mul_f32_e32 v61, v61, v9
	v_mul_f32_e32 v62, v62, v9
	v_mul_f32_e32 v63, v63, v9
	v_mul_f32_e32 v64, v64, v9
	v_mul_f32_e32 v65, v65, v9
	v_mul_f32_e32 v66, v66, v9
	v_mul_f32_e32 v67, v67, v9
	v_mul_f32_e32 v68, v68, v9
	v_mul_f32_e32 v69, v69, v9
	v_mul_f32_e32 v70, v70, v9
	v_mul_f32_e32 v71, v71, v9
	v_mul_f32_e32 v72, v72, v9
	v_mul_f32_e32 v73, v73, v9
	v_mul_f32_e32 v74, v74, v9
	v_mul_f32_e32 v75, v75, v9
	v_mul_f32_e32 v76, v76, v9
	v_mul_f32_e32 v77, v77, v9
	v_mul_f32_e32 v78, v78, v9
	v_mul_f32_e32 v79, v79, v9
	v_mul_f32_e32 v171, v171, v9
	v_mul_f32_e32 v170, v170, v9
	v_sub_f32_e32 v80, 0, v214
	v_mov_b32_e32 v81, v80
	v_mov_b32_e32 v82, v80
	v_mov_b32_e32 v83, v80
	v_mov_b32_e32 v84, v80
	v_mov_b32_e32 v85, v80
	v_mov_b32_e32 v86, v80
	v_mov_b32_e32 v87, v80
	v_mov_b32_e32 v88, v80
	v_mov_b32_e32 v89, v80
	v_mov_b32_e32 v90, v80
	v_mov_b32_e32 v91, v80
	v_mov_b32_e32 v92, v80
	v_mov_b32_e32 v93, v80
	v_mov_b32_e32 v94, v80
	v_mov_b32_e32 v95, v80
	v_exp_f32_e32 v172, v128
	v_exp_f32_e32 v173, v129
	v_exp_f32_e32 v174, v130
	v_exp_f32_e32 v175, v131
	v_exp_f32_e32 v176, v132
	v_exp_f32_e32 v177, v133
	v_exp_f32_e32 v178, v134
	v_exp_f32_e32 v179, v135
	v_exp_f32_e32 v180, v136
	v_exp_f32_e32 v181, v137
	v_exp_f32_e32 v182, v138
	v_exp_f32_e32 v183, v139
	v_exp_f32_e32 v188, v140
	v_exp_f32_e32 v189, v141
	v_exp_f32_e32 v190, v142
	v_exp_f32_e32 v191, v143
	v_cvt_pk_bf16_f32 v222, v172, v173
	v_add_f32_e32 v2, v172, v174
	v_add_f32_e32 v6, v173, v175
	v_cvt_pk_bf16_f32 v223, v174, v175
	v_cvt_pk_bf16_f32 v224, v176, v177
	v_add_f32_e32 v2, v176, v2
	v_add_f32_e32 v6, v177, v6
	v_cvt_pk_bf16_f32 v225, v178, v179
	v_add_f32_e32 v2, v178, v2
	v_add_f32_e32 v6, v179, v6
	v_cvt_pk_bf16_f32 v226, v180, v181
	v_add_f32_e32 v2, v180, v2
	v_add_f32_e32 v6, v181, v6
	v_cvt_pk_bf16_f32 v227, v182, v183
	v_add_f32_e32 v2, v182, v2
	v_add_f32_e32 v6, v183, v6
	v_cvt_pk_bf16_f32 v228, v188, v189
	v_add_f32_e32 v2, v188, v2
	v_add_f32_e32 v6, v189, v6
	v_cvt_pk_bf16_f32 v229, v190, v191
; #define LAS __attribute__((address_space(3)))
; __device__ __forceinline__ unsigned cvtpk(float lo, float hi) { const f32x2_t v = {lo, hi}; const bf16x2_t b = __builtin_convertvector(v, bf16x2_t); return __builtin_bit_cast(unsigned, b); }
; __device__ __forceinline__ void attn_pass2b(f32x16 (&o)[2][2], const bf16_t* qrow0, const bf16_t* Kb, const bf16_t* Vtb, int ka, int kb, LAS unsigned char* lds) {
;     ...
;         bf16x8 pk[2][4];
; #pragma unroll
;         for (int rb = 0; rb < 2; ++rb) {
;             f32x16& p0 = p[rb][0]; f32x16& p1 = p[rb][1];
;             float rs0 = 0.f, rs1 = 0.f;
; #pragma unroll
;             for (int r = 0; r < 16; ++r) { p0[r] = __builtin_amdgcn_exp2f(p0[r]); p1[r] = __builtin_amdgcn_exp2f(p1[r]); rs0 += p0[r]; rs1 += p1[r]; }
;             lrun[rb] += rs0 + rs1;
;             u32x4 w;
;             w.x = cvtpk(p0[0], p0[1]); w.y = cvtpk(p0[2], p0[3]); w.z = cvtpk(p0[4], p0[5]); w.w = cvtpk(p0[6], p0[7]); pk[rb][0] = __builtin_bit_cast(bf16x8, w);
;             w.x = cvtpk(p0[8], p0[9]); w.y = cvtpk(p0[10], p0[11]); w.z = cvtpk(p0[12], p0[13]); w.w = cvtpk(p0[14], p0[15]); pk[rb][1] = __builtin_bit_cast(bf16x8, w);
;             w.x = cvtpk(p1[0], p1[1]); w.y = cvtpk(p1[2], p1[3]); w.z = cvtpk(p1[4], p1[5]); w.w = cvtpk(p1[6], p1[7]); pk[rb][2] = __builtin_bit_cast(bf16x8, w);
;             w.x = cvtpk(p1[8], p1[9]); w.y = cvtpk(p1[10], p1[11]); w.z = cvtpk(p1[12], p1[13]); w.w = cvtpk(p1[14], p1[15]); pk[rb][3] = __builtin_bit_cast(bf16x8, w);
;         }
; #pragma unroll
;         for (int db = 0; db < 2; ++db) {
;             bf16x8 vfr[4];
; #pragma unroll
;             for (int c = 0; c < 4; ++c) vfr[c] = *(const LAS bf16x8*)(Vl + ((32 * db + r32) * VP + 16 * c + 8 * hi) * 2);
; #pragma unroll
;             for (int c = 0; c < 4; ++c) {
;                 o[0][db] = __builtin_amdgcn_mfma_f32_32x32x16_bf16(vfr[c], pk[0][c], o[0][db], 0, 0, 0);
;                 o[1][db] = __builtin_amdgcn_mfma_f32_32x32x16_bf16(vfr[c], pk[1][c], o[1][db], 0, 0, 0);
;             }
;         }
	v_add_f32_e32 v2, v190, v2
	v_add_f32_e32 v6, v191, v6
	v_exp_f32_e32 v192, v144
	v_exp_f32_e32 v193, v145
	v_exp_f32_e32 v194, v146
	v_exp_f32_e32 v195, v147
	v_exp_f32_e32 v196, v148
	v_exp_f32_e32 v197, v149
	v_exp_f32_e32 v198, v150
	v_exp_f32_e32 v199, v151
	v_exp_f32_e32 v200, v152
	v_exp_f32_e32 v201, v153
	v_exp_f32_e32 v202, v154
	v_exp_f32_e32 v203, v155
	v_exp_f32_e32 v204, v156
	v_exp_f32_e32 v205, v157
	v_exp_f32_e32 v206, v158
	v_exp_f32_e32 v207, v159
	v_cvt_pk_bf16_f32 v230, v192, v193
	v_add_f32_e32 v3, v192, v194
	v_add_f32_e32 v7, v193, v195
	v_cvt_pk_bf16_f32 v231, v194, v195
	v_cvt_pk_bf16_f32 v232, v196, v197
	v_add_f32_e32 v3, v196, v3
	v_add_f32_e32 v7, v197, v7
	v_cvt_pk_bf16_f32 v233, v198, v199
	v_add_f32_e32 v3, v198, v3
	v_add_f32_e32 v7, v199, v7
	v_cvt_pk_bf16_f32 v234, v200, v201
	v_add_f32_e32 v3, v200, v3
	v_add_f32_e32 v7, v201, v7
	v_cvt_pk_bf16_f32 v235, v202, v203
	v_add_f32_e32 v3, v202, v3
	v_add_f32_e32 v7, v203, v7
	v_cvt_pk_bf16_f32 v236, v204, v205
	v_add_f32_e32 v3, v204, v3
	v_add_f32_e32 v7, v205, v7
	v_cvt_pk_bf16_f32 v237, v206, v207
	v_add_f32_e32 v3, v206, v3
	v_add_f32_e32 v7, v207, v7
	v_exp_f32_e32 v172, v112
	v_exp_f32_e32 v173, v113
	v_exp_f32_e32 v174, v114
	v_exp_f32_e32 v175, v115
	v_exp_f32_e32 v176, v116
	v_exp_f32_e32 v177, v117
	v_exp_f32_e32 v178, v118
	v_exp_f32_e32 v179, v119
	v_exp_f32_e32 v180, v120
	v_exp_f32_e32 v181, v121
	v_exp_f32_e32 v182, v122
	v_exp_f32_e32 v183, v123
	v_exp_f32_e32 v188, v124
	v_exp_f32_e32 v189, v125
	v_exp_f32_e32 v190, v126
	v_exp_f32_e32 v191, v127
	v_cvt_pk_bf16_f32 v238, v172, v173
	v_add_f32_e32 v4, v172, v174
	v_add_f32_e32 v8, v173, v175
	v_cvt_pk_bf16_f32 v239, v174, v175
	v_cvt_pk_bf16_f32 v240, v176, v177
	v_add_f32_e32 v4, v176, v4
	v_add_f32_e32 v8, v177, v8
	v_cvt_pk_bf16_f32 v241, v178, v179
	v_add_f32_e32 v4, v178, v4
	v_add_f32_e32 v8, v179, v8
	v_cvt_pk_bf16_f32 v242, v180, v181
	v_add_f32_e32 v4, v180, v4
	v_add_f32_e32 v8, v181, v8
	v_cvt_pk_bf16_f32 v243, v182, v183
	v_add_f32_e32 v4, v182, v4
	v_add_f32_e32 v8, v183, v8
	v_cvt_pk_bf16_f32 v244, v188, v189
	v_add_f32_e32 v4, v188, v4
	v_add_f32_e32 v8, v189, v8
	v_cvt_pk_bf16_f32 v245, v190, v191
	v_add_f32_e32 v4, v190, v4
	v_add_f32_e32 v8, v191, v8
	v_exp_f32_e32 v192, v96
	v_exp_f32_e32 v193, v97
	v_exp_f32_e32 v194, v98
	v_exp_f32_e32 v195, v99
	v_exp_f32_e32 v196, v100
	v_exp_f32_e32 v197, v101
	v_exp_f32_e32 v198, v102
	v_exp_f32_e32 v199, v103
	v_exp_f32_e32 v200, v104
	v_exp_f32_e32 v201, v105
	v_exp_f32_e32 v202, v106
	v_exp_f32_e32 v203, v107
	v_exp_f32_e32 v204, v108
	v_exp_f32_e32 v205, v109
	v_exp_f32_e32 v206, v110
	v_exp_f32_e32 v207, v111
	v_cvt_pk_bf16_f32 v246, v192, v193
	v_add_f32_e32 v5, v192, v194
	v_add_f32_e32 v9, v193, v195
	v_cvt_pk_bf16_f32 v247, v194, v195
	v_cvt_pk_bf16_f32 v248, v196, v197
	v_add_f32_e32 v5, v196, v5
	v_add_f32_e32 v9, v197, v9
	v_cvt_pk_bf16_f32 v249, v198, v199
	v_add_f32_e32 v5, v198, v5
	v_add_f32_e32 v9, v199, v9
	v_cvt_pk_bf16_f32 v216, v200, v201
	v_add_f32_e32 v5, v200, v5
	v_add_f32_e32 v9, v201, v9
	v_cvt_pk_bf16_f32 v217, v202, v203
	v_add_f32_e32 v5, v202, v5
	v_add_f32_e32 v9, v203, v9
	v_cvt_pk_bf16_f32 v218, v204, v205
	v_add_f32_e32 v5, v204, v5
	v_add_f32_e32 v9, v205, v9
	v_cvt_pk_bf16_f32 v219, v206, v207
	v_add_f32_e32 v5, v206, v5
	v_add_f32_e32 v9, v207, v9
	v_add_f32_e32 v2, v6, v2
	v_add_f32_e32 v3, v7, v3
	v_add_f32_e32 v4, v8, v4
	v_add_f32_e32 v5, v9, v5
	v_add_f32_e32 v2, v3, v2
	v_add_f32_e32 v4, v5, v4
	v_max_f32_e32 v6, v2, v4
	s_branch .Lpb_tail
.Lpb_Xlast:
	ds_read_b128 v[96:99], v157 offset:9216
	ds_read_b128 v[100:103], v157 offset:9248
	ds_read_b128 v[104:107], v157 offset:9280
	ds_read_b128 v[108:111], v157 offset:9312
	ds_read_b128 v[112:115], v157 offset:13824
	ds_read_b128 v[116:119], v157 offset:13856
	ds_read_b128 v[120:123], v157 offset:13888
	ds_read_b128 v[124:127], v157 offset:13920
	s_waitcnt lgkmcnt(7)
	v_mfma_f32_32x32x16_bf16 v[48:63], v[96:99], v[222:225], v[48:63]
	v_mfma_f32_32x32x16_bf16 v[16:31], v[96:99], v[238:241], v[16:31]
	s_waitcnt lgkmcnt(6)
	v_mfma_f32_32x32x16_bf16 v[48:63], v[100:103], v[226:229], v[48:63]
	v_mfma_f32_32x32x16_bf16 v[16:31], v[100:103], v[242:245], v[16:31]
	s_waitcnt lgkmcnt(5)
	v_mfma_f32_32x32x16_bf16 v[48:63], v[104:107], v[230:233], v[48:63]
	v_mfma_f32_32x32x16_bf16 v[16:31], v[104:107], v[246:249], v[16:31]
	s_waitcnt lgkmcnt(4)
	v_mfma_f32_32x32x16_bf16 v[48:63], v[108:111], v[234:237], v[48:63]
	v_mfma_f32_32x32x16_bf16 v[16:31], v[108:111], v[216:219], v[16:31]
	s_waitcnt lgkmcnt(3)
	v_mfma_f32_32x32x16_bf16 v[64:79], v[112:115], v[222:225], v[64:79]
	v_mfma_f32_32x32x16_bf16 v[32:47], v[112:115], v[238:241], v[32:47]
	s_waitcnt lgkmcnt(2)
	v_mfma_f32_32x32x16_bf16 v[64:79], v[116:119], v[226:229], v[64:79]
	v_mfma_f32_32x32x16_bf16 v[32:47], v[116:119], v[242:245], v[32:47]
	s_waitcnt lgkmcnt(1)
	v_mfma_f32_32x32x16_bf16 v[64:79], v[120:123], v[230:233], v[64:79]
	v_mfma_f32_32x32x16_bf16 v[32:47], v[120:123], v[246:249], v[32:47]
	s_waitcnt lgkmcnt(0)
	v_mfma_f32_32x32x16_bf16 v[64:79], v[124:127], v[234:237], v[64:79]
	v_mfma_f32_32x32x16_bf16 v[32:47], v[124:127], v[216:219], v[32:47]
	s_setprio 0
	s_barrier
	s_cmp_lg_u32 s13, 0
	s_cbranch_scc1 .Lpb_done
	s_barrier
.Lpb_done:
	v_mbcnt_hi_u32_b32 v252, -1, v220
	v_and_b32_e32 v174, 64, v252
	v_xor_b32_e32 v253, 32, v252
	v_add_u32_e32 v254, 64, v174
	s_branch .LBB0_415

; #define LAS __attribute__((address_space(3)))
; template <int DV> ...
;     ...
; #pragma unroll
;     for (int i = 0; i < DV / 32; ++i)
; #pragma unroll
;         for (int r = 0; r < 16; ++r) o[i][r] = 0.f;
;     float mref = has_sink ? m_init : 0.f, lrun = l_init;
;     bool first = !has_sink;
;     f32x16 negm;
; #pragma unroll
;     for (int r = 0; r < 16; ++r) negm[r] = -mref;
;     const int n0 = (s0b - s0a) >> 6, nt = n0 + ((s1b - s1a) >> 6);
;     const int lrow = tid >> 3, lch = tid & 7;
;     const bf16_t* kg = Kb + (size_t)lrow * kpitch + lch * 8;
;     const bf16_t* vg = Vtb + (size_t)lrow * NKV + lch * 8;
;     const int prow = (lrow & ~12) | ((lrow & 4) << 1) | ((lrow & 8) >> 1);
;     const unsigned kst = (unsigned)((prow * KP + lch * 8) * 2), vst = (unsigned)(KBUFB + (lrow * VP + lch * 8) * 2);
;     u32x4 kr, vr0, vr1;
;     {
;         const int k0 = (0 < n0) ? s0a : s1a;
;         kr = *(const u32x4*)(kg + (size_t)k0 * kpitch); vr0 = *(const u32x4*)(vg + k0);
;         if (DV == 128) vr1 = *(const u32x4*)(vg + (size_t)64 * NKV + k0);
;         *(LAS u32x4*)(lds + kst) = kr;
;         *(LAS u32x4*)(lds + vst) = vr0;
;         if (DV == 128) *(LAS u32x4*)(lds + vst + 64 * VP * 2) = vr1;
;     }
;     __syncthreads();
.LBB0_421:
	v_mov_b32_e32 v17, 0
	s_andn2_b64 vcc, exec, s[4:5]
	v_mov_b32_e32 v16, 0
	v_mov_b32_e32 v15, 0
	v_mov_b32_e32 v14, 0
	v_mov_b32_e32 v13, 0
	v_mov_b32_e32 v12, 0
	v_mov_b32_e32 v11, 0
	v_mov_b32_e32 v10, 0
	v_mov_b32_e32 v9, 0
	v_mov_b32_e32 v8, 0
	v_mov_b32_e32 v7, 0
	v_mov_b32_e32 v6, 0
	v_mov_b32_e32 v5, 0
	v_mov_b32_e32 v4, 0
	v_mov_b32_e32 v3, 0
	v_mov_b32_e32 v2, 0
	v_mov_b32_e32 v33, 0
	v_mov_b32_e32 v32, 0
	v_mov_b32_e32 v31, 0
	v_mov_b32_e32 v30, 0
	v_mov_b32_e32 v29, 0
	v_mov_b32_e32 v28, 0
	v_mov_b32_e32 v27, 0
	v_mov_b32_e32 v26, 0
	v_mov_b32_e32 v25, 0
	v_mov_b32_e32 v24, 0
	v_mov_b32_e32 v23, 0
	v_mov_b32_e32 v22, 0
	v_mov_b32_e32 v21, 0
	v_mov_b32_e32 v20, 0
	v_mov_b32_e32 v19, 0
	v_mov_b32_e32 v18, 0
	v_mov_b32_e32 v65, 0
	v_mov_b32_e32 v64, 0
	v_mov_b32_e32 v63, 0
	v_mov_b32_e32 v62, 0
	v_mov_b32_e32 v61, 0
	v_mov_b32_e32 v60, 0
	v_mov_b32_e32 v59, 0
	v_mov_b32_e32 v58, 0
	v_mov_b32_e32 v57, 0
	v_mov_b32_e32 v56, 0
	v_mov_b32_e32 v55, 0
	v_mov_b32_e32 v54, 0
	v_mov_b32_e32 v53, 0
	v_mov_b32_e32 v52, 0
	v_mov_b32_e32 v51, 0
	v_mov_b32_e32 v50, 0
	v_mov_b32_e32 v49, 0
	v_mov_b32_e32 v48, 0
	v_mov_b32_e32 v47, 0
	v_mov_b32_e32 v46, 0
	v_mov_b32_e32 v45, 0
	v_mov_b32_e32 v44, 0
	v_mov_b32_e32 v43, 0
	v_mov_b32_e32 v42, 0
	v_mov_b32_e32 v41, 0
	v_mov_b32_e32 v40, 0
	v_mov_b32_e32 v39, 0
	v_mov_b32_e32 v38, 0
	v_mov_b32_e32 v37, 0
	v_mov_b32_e32 v36, 0
	v_mov_b32_e32 v35, 0
	v_mov_b32_e32 v34, 0
	v_mov_b32_e32 v189, 0
	s_cbranch_vccnz .LBB0_437
	v_and_b32_e32 v82, 31, v253
	v_bfe_u32 v83, v253, 5, 1
	v_lshlrev_b32_e32 v83, 3, v83
	v_mul_u32_u24_e32 v84, 0x48, v82
	v_add_lshl_u32 v194, v83, v84, 1
	v_mul_u32_u24_e32 v196, 0x90, v82
	v_and_b32_e32 v84, 64, v185
	v_xor_b32_e32 v190, 32, v185
	v_add_u32_e32 v191, 64, v84
	v_cmp_lt_i32_e32 vcc, v190, v191
	s_nop 1
	v_cndmask_b32_e32 v82, v185, v190, vcc
	v_lshlrev_b32_e32 v195, 2, v82
	s_mov_b32 s77, s76
	s_mov_b32 s78, s76
	s_mov_b32 s79, s76
	s_mov_b32 s80, s76
	s_mov_b32 s81, s76
	s_mov_b32 s82, s76
	s_mov_b32 s83, s76
	s_mov_b32 s84, s76
	s_mov_b32 s85, s76
	s_mov_b32 s86, s76
	s_mov_b32 s87, s76
	s_mov_b32 s88, s76
	s_mov_b32 s89, s76
	s_mov_b32 s90, s76
	s_mov_b32 s91, s76
	v_mov_b32_e32 v66, s76
	v_mov_b32_e32 v67, s76
	v_mov_b32_e32 v68, s76
	v_mov_b32_e32 v69, s76
	v_mov_b32_e32 v70, s76
	v_mov_b32_e32 v71, s76
	v_mov_b32_e32 v72, s76
	v_mov_b32_e32 v73, s76
	v_mov_b32_e32 v74, s76
	v_mov_b32_e32 v75, s76
	v_mov_b32_e32 v76, s76
	v_mov_b32_e32 v77, s76
	v_mov_b32_e32 v78, s76
	v_mov_b32_e32 v79, s76
	v_mov_b32_e32 v80, s76
	v_mov_b32_e32 v81, s76
	v_mov_b32_e32 v188, 0
	s_cmp_lt_i32 s26, 2
	s_cbranch_scc1 .Lpa_pre_done
	s_mov_b32 s3, 1
	s_cmp_lt_i32 s3, s1
	s_cselect_b32 s4, 0, s1
	s_cselect_b32 s5, s94, 0x2000
	s_sub_i32 s4, s3, s4
	s_lshl_b32 s4, s4, 6
	s_add_i32 s4, s5, s4
	s_ashr_i32 s5, s4, 31
	s_lshl_b64 s[30:31], s[4:5], 10
	v_lshl_add_u64 v[142:143], v[180:181], 0, s[30:31]
	global_load_dwordx4 v[130:133], v[142:143], off
	s_lshl_b64 s[30:31], s[4:5], 1
	v_lshl_add_u64 v[142:143], v[182:183], 0, s[30:31]
	v_lshl_add_u64 v[144:145], v[186:187], 0, s[30:31]
	global_load_dwordx4 v[134:137], v[142:143], off
	global_load_dwordx4 v[138:141], v[144:145], off
.Lpa_pre_done:
	s_getreg_b32 s2, hwreg(HW_REG_HW_ID, 4, 2)
	v_readfirstlane_b32 s3, v253
	s_lshr_b32 s3, s3, 6
	s_lshl_b32 s4, s3, 2
	s_add_i32 s4, s4, 0x20200
	v_mov_b32_e32 v82, s2
	v_mov_b32_e32 v83, s4
	ds_write_b32 v83, v82
	s_waitcnt lgkmcnt(0)
	s_barrier
	v_mov_b32_e32 v83, 0x20200
	ds_read_b128 v[84:87], v83
	ds_read_b128 v[88:91], v83 offset:16
	s_mov_b32 s25, 0
	s_waitcnt lgkmcnt(0)
	v_readfirstlane_b32 s4, v84
	s_cmp_eq_u32 s4, s2
	s_cselect_b32 s4, 1, 0
	s_cmp_gt_u32 s3, 0
	s_cselect_b32 s5, 1, 0
	s_and_b32 s4, s4, s5
	s_add_i32 s25, s25, s4
	v_readfirstlane_b32 s4, v85
	s_cmp_eq_u32 s4, s2
	s_cselect_b32 s4, 1, 0
	s_cmp_gt_u32 s3, 1
	s_cselect_b32 s5, 1, 0
	s_and_b32 s4, s4, s5
	s_add_i32 s25, s25, s4
	v_readfirstlane_b32 s4, v86
	s_cmp_eq_u32 s4, s2
	s_cselect_b32 s4, 1, 0
	s_cmp_gt_u32 s3, 2
	s_cselect_b32 s5, 1, 0
	s_and_b32 s4, s4, s5
	s_add_i32 s25, s25, s4
	v_readfirstlane_b32 s4, v87
	s_cmp_eq_u32 s4, s2
	s_cselect_b32 s4, 1, 0
	s_cmp_gt_u32 s3, 3
	s_cselect_b32 s5, 1, 0
	s_and_b32 s4, s4, s5
	s_add_i32 s25, s25, s4
	v_readfirstlane_b32 s4, v88
	s_cmp_eq_u32 s4, s2
	s_cselect_b32 s4, 1, 0
	s_cmp_gt_u32 s3, 4
	s_cselect_b32 s5, 1, 0
	s_and_b32 s4, s4, s5
	s_add_i32 s25, s25, s4
	v_readfirstlane_b32 s4, v89
	s_cmp_eq_u32 s4, s2
	s_cselect_b32 s4, 1, 0
	s_cmp_gt_u32 s3, 5
	s_cselect_b32 s5, 1, 0
	s_and_b32 s4, s4, s5
	s_add_i32 s25, s25, s4
	v_readfirstlane_b32 s4, v90
	s_cmp_eq_u32 s4, s2
	s_cselect_b32 s4, 1, 0
	s_cmp_gt_u32 s3, 6
	s_cselect_b32 s5, 1, 0
	s_and_b32 s4, s4, s5
	s_add_i32 s25, s25, s4
	s_mov_b32 s22, 0
	s_cmp_eq_u32 s25, 0
	s_cbranch_scc1 .Lpa_X
	s_barrier
; #define LAS __attribute__((address_space(3)))
; template <int DV> ...
;     ...
;     for (int t = 0; t < nt; ++t) {
;         const int k0 = (t < n0) ? (s0a + (t << 6)) : (s1a + ((t - n0) << 6));
;         const bool more = (t + 1 < nt);
;         if (more) {
;             const int k1 = (t + 1 < n0) ? (s0a + ((t + 1) << 6)) : (s1a + ((t + 1 - n0) << 6));
;             kr = *(const u32x4*)(kg + (size_t)k1 * kpitch); vr0 = *(const u32x4*)(vg + k1);
;             if (DV == 128) vr1 = *(const u32x4*)(vg + (size_t)64 * NKV + k1);
;         }
;         const LAS unsigned char* Kl = lds + (t & 1) * ABUFB;
;         const LAS unsigned char* Vl = Kl + KBUFB;
;         const bool masked = win && (t < n0);
;         const bool skip = masked && ((k0 + 63 < qw0 - 128) || (k0 > qw0 + 31 + 128));
;         if (!skip) {
;             f32x16 p0, p1;
;             {
;                 bf16x8 kf[8];
; #pragma unroll
;                 for (int d0 = 0; d0 < 4; ++d0) {
;                     kf[2 * d0] = *(const LAS bf16x8*)(Kl + (r32 * KP + 16 * d0 + 8 * hi) * 2);
;                     kf[2 * d0 + 1] = *(const LAS bf16x8*)(Kl + ((32 + r32) * KP + 16 * d0 + 8 * hi) * 2);
;                 }
;                 __builtin_amdgcn_sched_barrier(0);
;                 p0 = __builtin_amdgcn_mfma_f32_32x32x16_bf16(kf[0], qf[0], negm, 0, 0, 0); p1 = __builtin_amdgcn_mfma_f32_32x32x16_bf16(kf[1], qf[0], negm, 0, 0, 0);
; #pragma unroll
;                 for (int d0 = 1; d0 < 4; ++d0) { p0 = __builtin_amdgcn_mfma_f32_32x32x16_bf16(kf[2 * d0], qf[d0], p0, 0, 0, 0); p1 = __builtin_amdgcn_mfma_f32_32x32x16_bf16(kf[2 * d0 + 1], qf[d0], p1, 0, 0, 0); }
;     ...
;             if (DV == 128) {
;                 bf16x8 vfb[8];
; #pragma unroll
;                 for (int db = 2; db < 4; ++db)
; #pragma unroll
;                     for (int c = 0; c < 4; ++c) vfb[(db - 2) * 4 + c] = *(const LAS bf16x8*)(Vl + ((32 * db + r32) * VP + 16 * c + 8 * hi) * 2);
; #pragma unroll
;                 for (int db = 0; db < 2; ++db)
; #pragma unroll
;                     for (int c = 0; c < 4; ++c) {
;                         o[db] = __builtin_amdgcn_mfma_f32_32x32x16_bf16(vfa[db * 4 + c], pk[c], o[db], 0, 0, 0);
;                     }
;                 __builtin_amdgcn_sched_barrier(0);
; #pragma unroll
;                 for (int db = 2; db < DV / 32; ++db)
; #pragma unroll
;                     for (int c = 0; c < 4; ++c) {
.Lpa_X:
	s_setprio 1
	s_and_b32 s4, s22, 1
	s_mul_i32 s23, s4, 0x6c00
	s_sub_i32 s24, 0x6c00, s23
	v_add_u32_e32 v199, s23, v194
	s_add_i32 s3, s22, 1
	s_mul_hi_u32 s4, s3, 0x55555556
	s_mul_i32 s4, s4, 3
	s_sub_i32 s4, s3, s4
	s_mul_i32 s5, s4, 0x6c00
	v_add_u32_e32 v218, s24, v192
	v_add_u32_e32 v219, s5, v193
	s_cmp_eq_u32 s22, 0
	s_cbranch_scc1 .Lpa_Xfirst
	s_cmp_ge_i32 s22, s26
	s_cbranch_scc1 .Lpa_Xlast
	s_waitcnt lgkmcnt(11)
	v_mfma_f32_32x32x16_bf16 v[2:17], v[82:85], v[200:203], v[2:17]
	ds_read_b128 v[158:161], v197 offset:23040
	s_waitcnt lgkmcnt(11)
	v_mfma_f32_32x32x16_bf16 v[2:17], v[86:89], v[204:207], v[2:17]
	ds_read_b128 v[162:165], v197 offset:23072
	s_waitcnt lgkmcnt(11)
	v_mfma_f32_32x32x16_bf16 v[2:17], v[90:93], v[210:213], v[2:17]
	ds_read_b128 v[166:169], v197 offset:23104
	s_waitcnt lgkmcnt(11)
	v_mfma_f32_32x32x16_bf16 v[2:17], v[94:97], v[214:217], v[2:17]
	ds_read_b128 v[170:173], v197 offset:23136
	s_waitcnt vmcnt(0)
	s_waitcnt lgkmcnt(11)
	v_mfma_f32_32x32x16_bf16 v[18:33], v[98:101], v[200:203], v[18:33]
	ds_write_b128 v218, v[130:133]
	s_waitcnt lgkmcnt(11)
	v_mfma_f32_32x32x16_bf16 v[18:33], v[102:105], v[204:207], v[18:33]
	ds_write_b128 v219, v[134:137] offset:9216
	s_waitcnt lgkmcnt(11)
	v_mfma_f32_32x32x16_bf16 v[18:33], v[106:109], v[210:213], v[18:33]
	ds_write_b128 v219, v[138:141] offset:18432
	s_waitcnt lgkmcnt(11)
	v_mfma_f32_32x32x16_bf16 v[18:33], v[110:113], v[214:217], v[18:33]
	s_add_i32 s3, s22, 2
	s_cmp_ge_i32 s3, s26
	s_cbranch_scc1 .Lpa_noload_mid
	s_cmp_lt_i32 s3, s1
	s_cselect_b32 s4, 0, s1
	s_cselect_b32 s5, s94, 0x2000
	s_sub_i32 s4, s3, s4
	s_lshl_b32 s4, s4, 6
	s_add_i32 s4, s5, s4
	s_ashr_i32 s5, s4, 31
	s_lshl_b64 s[30:31], s[4:5], 10
	v_lshl_add_u64 v[218:219], v[180:181], 0, s[30:31]
	s_lshl_b64 s[30:31], s[4:5], 1
	v_lshl_add_u64 v[220:221], v[182:183], 0, s[30:31]
	global_load_dwordx4 v[130:133], v[218:219], off
	v_lshl_add_u64 v[218:219], v[186:187], 0, s[30:31]
	global_load_dwordx4 v[134:137], v[220:221], off
	global_load_dwordx4 v[138:141], v[218:219], off
.Lpa_noload_mid:
	s_waitcnt lgkmcnt(10)
	v_mfma_f32_32x32x16_bf16 v[50:65], v[142:145], v[200:203], v[50:65]
	ds_read_b128 v[142:145], v199
	s_waitcnt lgkmcnt(10)
	v_mfma_f32_32x32x16_bf16 v[50:65], v[146:149], v[204:207], v[50:65]
	ds_read_b128 v[146:149], v199 offset:4608
	s_waitcnt lgkmcnt(10)
	v_mfma_f32_32x32x16_bf16 v[50:65], v[150:153], v[210:213], v[50:65]
	ds_read_b128 v[150:153], v199 offset:32
	s_waitcnt lgkmcnt(10)
	v_mfma_f32_32x32x16_bf16 v[50:65], v[154:157], v[214:217], v[50:65]
	ds_read_b128 v[154:157], v199 offset:4640
	s_waitcnt lgkmcnt(10)
	v_mfma_f32_32x32x16_bf16 v[34:49], v[158:161], v[200:203], v[34:49]
	ds_read_b128 v[158:161], v199 offset:64
	s_waitcnt lgkmcnt(10)
	v_mfma_f32_32x32x16_bf16 v[34:49], v[162:165], v[204:207], v[34:49]
	ds_read_b128 v[162:165], v199 offset:4672
	s_waitcnt lgkmcnt(10)
	v_mfma_f32_32x32x16_bf16 v[34:49], v[166:169], v[210:213], v[34:49]
	ds_read_b128 v[166:169], v199 offset:96
	s_waitcnt lgkmcnt(10)
	v_mfma_f32_32x32x16_bf16 v[34:49], v[170:173], v[214:217], v[34:49]
	ds_read_b128 v[170:173], v199 offset:4704
	s_waitcnt lgkmcnt(7)
	v_mfma_f32_32x32x16_bf16 v[98:113], v[142:145], v[126:129], v[66:81]
	s_waitcnt lgkmcnt(6)
	v_mfma_f32_32x32x16_bf16 v[82:97], v[146:149], v[126:129], v[66:81]
	s_waitcnt lgkmcnt(5)
	v_mfma_f32_32x32x16_bf16 v[98:113], v[150:153], v[122:125], v[98:113]
	s_waitcnt lgkmcnt(4)
	v_mfma_f32_32x32x16_bf16 v[82:97], v[154:157], v[122:125], v[82:97]
	s_waitcnt lgkmcnt(3)
	v_mfma_f32_32x32x16_bf16 v[98:113], v[158:161], v[118:121], v[98:113]
	s_waitcnt lgkmcnt(2)
	v_mfma_f32_32x32x16_bf16 v[82:97], v[162:165], v[118:121], v[82:97]
	s_waitcnt lgkmcnt(1)
	v_mfma_f32_32x32x16_bf16 v[98:113], v[166:169], v[114:117], v[98:113]
	s_waitcnt lgkmcnt(0)
	v_mfma_f32_32x32x16_bf16 v[82:97], v[170:173], v[114:117], v[82:97]
	s_barrier
	s_branch .Lpa_Y
.Lpa_Xfirst:
	ds_read_b128 v[142:145], v199
	ds_read_b128 v[146:149], v199 offset:4608
	ds_read_b128 v[150:153], v199 offset:32
	ds_read_b128 v[154:157], v199 offset:4640
	ds_read_b128 v[158:161], v199 offset:64
	ds_read_b128 v[162:165], v199 offset:4672
	ds_read_b128 v[166:169], v199 offset:96
	ds_read_b128 v[170:173], v199 offset:4704
	s_waitcnt lgkmcnt(7)
	v_mfma_f32_32x32x16_bf16 v[98:113], v[142:145], v[126:129], v[66:81]
	s_waitcnt lgkmcnt(6)
	v_mfma_f32_32x32x16_bf16 v[82:97], v[146:149], v[126:129], v[66:81]
	s_waitcnt lgkmcnt(5)
	v_mfma_f32_32x32x16_bf16 v[98:113], v[150:153], v[122:125], v[98:113]
	s_waitcnt lgkmcnt(4)
	v_mfma_f32_32x32x16_bf16 v[82:97], v[154:157], v[122:125], v[82:97]
	s_waitcnt lgkmcnt(3)
	v_mfma_f32_32x32x16_bf16 v[98:113], v[158:161], v[118:121], v[98:113]
	s_waitcnt lgkmcnt(2)
	v_mfma_f32_32x32x16_bf16 v[82:97], v[162:165], v[118:121], v[82:97]
	s_waitcnt lgkmcnt(1)
	v_mfma_f32_32x32x16_bf16 v[98:113], v[166:169], v[114:117], v[98:113]
	s_waitcnt lgkmcnt(0)
	v_mfma_f32_32x32x16_bf16 v[82:97], v[170:173], v[114:117], v[82:97]
	s_waitcnt vmcnt(0)
	s_cmp_lt_i32 s26, 2
	s_cbranch_scc1 .Lpa_nokw
	ds_write_b128 v218, v[130:133]
	ds_write_b128 v219, v[134:137] offset:9216
	ds_write_b128 v219, v[138:141] offset:18432
.Lpa_nokw:
	s_add_i32 s3, s22, 2
	s_cmp_ge_i32 s3, s26
	s_cbranch_scc1 .Lpa_noload_first
	s_cmp_lt_i32 s3, s1
	s_cselect_b32 s4, 0, s1
	s_cselect_b32 s5, s94, 0x2000
	s_sub_i32 s4, s3, s4
	s_lshl_b32 s4, s4, 6
	s_add_i32 s4, s5, s4
	s_ashr_i32 s5, s4, 31
	s_lshl_b64 s[30:31], s[4:5], 10
	v_lshl_add_u64 v[218:219], v[180:181], 0, s[30:31]
	s_lshl_b64 s[30:31], s[4:5], 1
	v_lshl_add_u64 v[220:221], v[182:183], 0, s[30:31]
	global_load_dwordx4 v[130:133], v[218:219], off
	v_lshl_add_u64 v[218:219], v[186:187], 0, s[30:31]
	global_load_dwordx4 v[134:137], v[220:221], off
	global_load_dwordx4 v[138:141], v[218:219], off

; __device__ __forceinline__ unsigned cvtpk(float lo, float hi) { const f32x2_t v = {lo, hi}; const bf16x2_t b = __builtin_convertvector(v, bf16x2_t); return __builtin_bit_cast(unsigned, b); }
; #define MX3(a, b, c) __builtin_fmaxf(__builtin_fmaxf((a), (b)), (c))
; #define MX3(a, b, c) __builtin_fmaxf(__builtin_fmaxf((a), (b)), (c))
; #define MX3(a, b, c) __builtin_fmaxf(__builtin_fmaxf((a), (b)), (c))
; template <int DV> ...
;     ...
;             float ma = MX3(p0[0], p0[1], p1[0]), mb = MX3(p0[2], p0[3], p1[1]); ma = MX3(ma, p1[2], p1[3]);
; #pragma unroll
;             for (int r = 4; r < 16; r += 4) { ma = MX3(ma, p0[r], p0[r + 1]); mb = MX3(mb, p0[r + 2], p0[r + 3]); ma = MX3(ma, p1[r], p1[r + 1]); mb = MX3(mb, p1[r + 2], p1[r + 3]); }
;     ...
;             float mx = fmaxf(ma, mb);
;             mx = fmaxf(mx, __shfl_xor(mx, 32));
;             if (first || __any(mx > 8.f)) {
;                 const float dl = first ? mx : fmaxf(mx, 0.f);
;                 const float alpha = first ? 1.f : __builtin_amdgcn_exp2f(-dl);
;                 mref += dl; lrun *= alpha;
; #pragma unroll
;                 for (int r = 0; r < 16; ++r) { p0[r] -= dl; p1[r] -= dl; negm[r] = -mref; }
; #pragma unroll
;                 for (int i = 0; i < DV / 32; ++i)
; #pragma unroll
;                     for (int r = 0; r < 16; ++r) o[i][r] *= alpha;
;                 first = false;
;             }
;             float rs0 = 0.f, rs1 = 0.f;
; #pragma unroll
;             for (int r = 0; r < 16; ++r) { p0[r] = __builtin_amdgcn_exp2f(p0[r]); p1[r] = __builtin_amdgcn_exp2f(p1[r]); rs0 += p0[r]; rs1 += p1[r]; }
;             lrun += rs0 + rs1;
;             bf16x8 pk[4];
;             { u32x4 w;
;               w.x = cvtpk(p0[0], p0[1]); w.y = cvtpk(p0[2], p0[3]); w.z = cvtpk(p0[4], p0[5]); w.w = cvtpk(p0[6], p0[7]); pk[0] = __builtin_bit_cast(bf16x8, w);
;               w.x = cvtpk(p0[8], p0[9]); w.y = cvtpk(p0[10], p0[11]); w.z = cvtpk(p0[12], p0[13]); w.w = cvtpk(p0[14], p0[15]); pk[1] = __builtin_bit_cast(bf16x8, w);
;               w.x = cvtpk(p1[0], p1[1]); w.y = cvtpk(p1[2], p1[3]); w.z = cvtpk(p1[4], p1[5]); w.w = cvtpk(p1[6], p1[7]); pk[2] = __builtin_bit_cast(bf16x8, w);
;               w.x = cvtpk(p1[8], p1[9]); w.y = cvtpk(p1[10], p1[11]); w.z = cvtpk(p1[12], p1[13]); w.w = cvtpk(p1[14], p1[15]); pk[3] = __builtin_bit_cast(bf16x8, w); }
.Lpa_Y:
	s_setprio 0
	s_nop 7
	s_cmp_eq_u32 s22, 0
	s_cbranch_scc1 .Lpa_slow
	v_exp_f32_e32 v142, v98
	v_exp_f32_e32 v143, v99
	v_exp_f32_e32 v144, v100
	v_exp_f32_e32 v145, v101
	v_exp_f32_e32 v146, v102
	v_exp_f32_e32 v147, v103
	v_exp_f32_e32 v148, v104
	v_exp_f32_e32 v149, v105
	v_exp_f32_e32 v150, v106
	v_exp_f32_e32 v151, v107
	v_exp_f32_e32 v152, v108
	v_exp_f32_e32 v153, v109
	v_exp_f32_e32 v154, v110
	v_exp_f32_e32 v155, v111
	v_exp_f32_e32 v156, v112
	v_exp_f32_e32 v157, v113
	v_exp_f32_e32 v158, v82
	v_exp_f32_e32 v159, v83
	v_exp_f32_e32 v160, v84
	v_exp_f32_e32 v161, v85
	v_exp_f32_e32 v162, v86
	v_exp_f32_e32 v163, v87
	v_exp_f32_e32 v164, v88
	v_exp_f32_e32 v165, v89
	v_exp_f32_e32 v166, v90
	v_exp_f32_e32 v167, v91
	v_exp_f32_e32 v168, v92
	v_exp_f32_e32 v169, v93
	v_exp_f32_e32 v170, v94
	v_exp_f32_e32 v171, v95
	v_exp_f32_e32 v172, v96
	v_exp_f32_e32 v173, v97
	v_add_f32_e32 v198, v142, v143
	v_add_f32_e32 v199, v158, v159
	v_add_f32_e32 v198, v144, v198
	v_add_f32_e32 v199, v160, v199
	v_add_f32_e32 v198, v145, v198
	v_add_f32_e32 v199, v161, v199
	v_add_f32_e32 v198, v146, v198
	v_add_f32_e32 v199, v162, v199
	v_add_f32_e32 v198, v147, v198
	v_add_f32_e32 v199, v163, v199
	v_add_f32_e32 v198, v148, v198
	v_add_f32_e32 v199, v164, v199
	v_add_f32_e32 v198, v149, v198
	v_add_f32_e32 v199, v165, v199
	v_add_f32_e32 v198, v150, v198
	v_add_f32_e32 v199, v166, v199
	v_add_f32_e32 v198, v151, v198
	v_add_f32_e32 v199, v167, v199
	v_add_f32_e32 v198, v152, v198
	v_add_f32_e32 v199, v168, v199
	v_add_f32_e32 v198, v153, v198
	v_add_f32_e32 v199, v169, v199
	v_add_f32_e32 v198, v154, v198
	v_add_f32_e32 v199, v170, v199
	v_add_f32_e32 v198, v155, v198
	v_add_f32_e32 v199, v171, v199
	v_add_f32_e32 v198, v156, v198
	v_add_f32_e32 v199, v172, v199
	v_add_f32_e32 v198, v157, v198
	v_add_f32_e32 v199, v173, v199
	v_add_f32_e32 v198, v199, v198
	v_cmp_lt_f32_e32 vcc, 0x43800000, v198
	v_cvt_pk_bf16_f32 v200, v142, v143
	v_cvt_pk_bf16_f32 v201, v144, v145
	v_cvt_pk_bf16_f32 v202, v146, v147
	v_cvt_pk_bf16_f32 v203, v148, v149
	v_cvt_pk_bf16_f32 v204, v150, v151
	v_cvt_pk_bf16_f32 v205, v152, v153
	v_cvt_pk_bf16_f32 v206, v154, v155
	v_cvt_pk_bf16_f32 v207, v156, v157
	v_cvt_pk_bf16_f32 v210, v158, v159
	v_cvt_pk_bf16_f32 v211, v160, v161
	v_cvt_pk_bf16_f32 v212, v162, v163
	v_cvt_pk_bf16_f32 v213, v164, v165
	v_cvt_pk_bf16_f32 v214, v166, v167
	v_cvt_pk_bf16_f32 v215, v168, v169
	v_cvt_pk_bf16_f32 v216, v170, v171
	v_cvt_pk_bf16_f32 v217, v172, v173
	s_cbranch_vccnz .Lpa_slow
.Lpa_tail:
	v_add_f32_e32 v189, v189, v198
	s_mul_hi_u32 s4, s22, 0x55555556
	s_mul_i32 s4, s4, 3
	s_sub_i32 s4, s22, s4
	s_mul_i32 s4, s4, 0x6c00
	v_add3_u32 v197, s4, v0, v196
	ds_read_b128 v[82:85], v197 offset:9216
	ds_read_b128 v[86:89], v197 offset:9248
	ds_read_b128 v[90:93], v197 offset:9280
	ds_read_b128 v[94:97], v197 offset:9312
	ds_read_b128 v[98:101], v197 offset:13824
	ds_read_b128 v[102:105], v197 offset:13856
	ds_read_b128 v[106:109], v197 offset:13888
	ds_read_b128 v[110:113], v197 offset:13920
	ds_read_b128 v[142:145], v197 offset:18432
	ds_read_b128 v[146:149], v197 offset:18464
	ds_read_b128 v[150:153], v197 offset:18496
	ds_read_b128 v[154:157], v197 offset:18528
	s_add_i32 s22, s22, 1
	s_barrier
	s_branch .Lpa_X

; #define LAS __attribute__((address_space(3)))
; __device__ __forceinline__ unsigned cvtpk(float lo, float hi) { const f32x2_t v = {lo, hi}; const bf16x2_t b = __builtin_convertvector(v, bf16x2_t); return __builtin_bit_cast(unsigned, b); }
; template <int DV> ...
;     ...
;             bf16x8 pk[4];
;             { u32x4 w;
;               w.x = cvtpk(p0[0], p0[1]); w.y = cvtpk(p0[2], p0[3]); w.z = cvtpk(p0[4], p0[5]); w.w = cvtpk(p0[6], p0[7]); pk[0] = __builtin_bit_cast(bf16x8, w);
;               w.x = cvtpk(p0[8], p0[9]); w.y = cvtpk(p0[10], p0[11]); w.z = cvtpk(p0[12], p0[13]); w.w = cvtpk(p0[14], p0[15]); pk[1] = __builtin_bit_cast(bf16x8, w);
;               w.x = cvtpk(p1[0], p1[1]); w.y = cvtpk(p1[2], p1[3]); w.z = cvtpk(p1[4], p1[5]); w.w = cvtpk(p1[6], p1[7]); pk[2] = __builtin_bit_cast(bf16x8, w);
;               w.x = cvtpk(p1[8], p1[9]); w.y = cvtpk(p1[10], p1[11]); w.z = cvtpk(p1[12], p1[13]); w.w = cvtpk(p1[14], p1[15]); pk[3] = __builtin_bit_cast(bf16x8, w); }
;             __builtin_amdgcn_sched_barrier(0);
;             if (DV == 128) {
;                 bf16x8 vfb[8];
; #pragma unroll
;                 for (int db = 2; db < 4; ++db)
; #pragma unroll
;                     for (int c = 0; c < 4; ++c) vfb[(db - 2) * 4 + c] = *(const LAS bf16x8*)(Vl + ((32 * db + r32) * VP + 16 * c + 8 * hi) * 2);
; #pragma unroll
;                 for (int db = 0; db < 2; ++db)
; #pragma unroll
;                     for (int c = 0; c < 4; ++c) {
;                         o[db] = __builtin_amdgcn_mfma_f32_32x32x16_bf16(vfa[db * 4 + c], pk[c], o[db], 0, 0, 0);
;                     }
;                 __builtin_amdgcn_sched_barrier(0);
; #pragma unroll
;                 for (int db = 2; db < DV / 32; ++db)
; #pragma unroll
;                     for (int c = 0; c < 4; ++c) {
;                         o[db] = __builtin_amdgcn_mfma_f32_32x32x16_bf16(vfb[(db - 2) * 4 + c], pk[c], o[db], 0, 0, 0);
;                     }
.Lpa_slowcvt:
	v_cvt_pk_bf16_f32 v200, v142, v143
	v_cvt_pk_bf16_f32 v201, v144, v145
	v_cvt_pk_bf16_f32 v202, v146, v147
	v_cvt_pk_bf16_f32 v203, v148, v149
	v_cvt_pk_bf16_f32 v204, v150, v151
	v_cvt_pk_bf16_f32 v205, v152, v153
	v_cvt_pk_bf16_f32 v206, v154, v155
	v_cvt_pk_bf16_f32 v207, v156, v157
	v_cvt_pk_bf16_f32 v210, v158, v159
	v_cvt_pk_bf16_f32 v211, v160, v161
	v_cvt_pk_bf16_f32 v212, v162, v163
	v_cvt_pk_bf16_f32 v213, v164, v165
	v_cvt_pk_bf16_f32 v214, v166, v167
	v_cvt_pk_bf16_f32 v215, v168, v169
	v_cvt_pk_bf16_f32 v216, v170, v171
	v_cvt_pk_bf16_f32 v217, v172, v173
	s_branch .Lpa_tail
.Lpa_Xlast:
	s_waitcnt lgkmcnt(11)
	v_mfma_f32_32x32x16_bf16 v[2:17], v[82:85], v[200:203], v[2:17]
	ds_read_b128 v[158:161], v197 offset:23040
	s_waitcnt lgkmcnt(11)
	v_mfma_f32_32x32x16_bf16 v[2:17], v[86:89], v[204:207], v[2:17]
	ds_read_b128 v[162:165], v197 offset:23072
	s_waitcnt lgkmcnt(11)
	v_mfma_f32_32x32x16_bf16 v[2:17], v[90:93], v[210:213], v[2:17]
	ds_read_b128 v[166:169], v197 offset:23104
	s_waitcnt lgkmcnt(11)
	v_mfma_f32_32x32x16_bf16 v[2:17], v[94:97], v[214:217], v[2:17]
	ds_read_b128 v[170:173], v197 offset:23136
	s_waitcnt lgkmcnt(11)
	v_mfma_f32_32x32x16_bf16 v[18:33], v[98:101], v[200:203], v[18:33]
	s_waitcnt lgkmcnt(10)
	v_mfma_f32_32x32x16_bf16 v[18:33], v[102:105], v[204:207], v[18:33]
	s_waitcnt lgkmcnt(9)
	v_mfma_f32_32x32x16_bf16 v[18:33], v[106:109], v[210:213], v[18:33]
	s_waitcnt lgkmcnt(8)
	v_mfma_f32_32x32x16_bf16 v[18:33], v[110:113], v[214:217], v[18:33]
	s_waitcnt lgkmcnt(7)
	v_mfma_f32_32x32x16_bf16 v[50:65], v[142:145], v[200:203], v[50:65]
	s_waitcnt lgkmcnt(6)
	v_mfma_f32_32x32x16_bf16 v[50:65], v[146:149], v[204:207], v[50:65]
	s_waitcnt lgkmcnt(5)
	v_mfma_f32_32x32x16_bf16 v[50:65], v[150:153], v[210:213], v[50:65]
	s_waitcnt lgkmcnt(4)
	v_mfma_f32_32x32x16_bf16 v[50:65], v[154:157], v[214:217], v[50:65]
	s_waitcnt lgkmcnt(3)
	v_mfma_f32_32x32x16_bf16 v[34:49], v[158:161], v[200:203], v[34:49]
	s_waitcnt lgkmcnt(2)
	v_mfma_f32_32x32x16_bf16 v[34:49], v[162:165], v[204:207], v[34:49]
	s_waitcnt lgkmcnt(1)
	v_mfma_f32_32x32x16_bf16 v[34:49], v[166:169], v[210:213], v[34:49]
	s_waitcnt lgkmcnt(0)
	v_mfma_f32_32x32x16_bf16 v[34:49], v[170:173], v[214:217], v[34:49]
	s_setprio 0
	s_barrier
	s_cmp_lg_u32 s25, 0
	s_cbranch_scc1 .Lpa_done
	s_barrier
